# as v131 but the two panel polls skip the L2-wiping acquire when all eight panel writers are proven (sum of squared XCC-id differences in the counter == 0) to sit behind the poller's own L2; otherwise
# speedup vs baseline: 1.0084x; 1.0081x over previous
.LBB0_898:
	s_mov_b64 s[2:3], s[74:75]
	s_waitcnt vmcnt(0)
	s_barrier
	s_getreg_b32 s0, hwreg(HW_REG_HW_ID, 0, 6)
	s_lshl_b32 s0, s0, 2
	s_and_b32 s0, s0, 0xfc
	s_add_i32 s0, s0, 0
	s_add_i32 s0, s0, 0x20200
	v_mov_b32_e32 v0, s0
	ds_read_b32 v0, v0
	v_readlane_b32 s0, v253, 12
	v_readlane_b32 s1, v253, 13
	s_add_i32 s0, s68, s0
	v_mbcnt_lo_u32_b32 v1, -1, 0
	v_mbcnt_hi_u32_b32 v1, -1, v1
	s_waitcnt lgkmcnt(0)
	v_readfirstlane_b32 s4, v0
	s_lshl_b32 s4, s4, 6
	v_sub_u32_e32 v0, 0, v1
	s_ashr_i32 s1, s0, 31
	s_lshl_b32 s100, s0, 2
	s_add_u32 s100, s100, 0xb400
	v_cmp_eq_u32_e32 vcc, s4, v0
	s_and_saveexec_b64 s[4:5], vcc
	s_cbranch_execz .LBB0_901
	s_mov_b64 s[8:9], exec
	v_mbcnt_lo_u32_b32 v0, s8, 0
	v_mbcnt_hi_u32_b32 v0, s9, v0
	v_cmp_eq_u32_e32 vcc, 0, v0
	s_and_b64 s[10:11], exec, vcc
	s_mov_b64 exec, s[10:11]
	s_cbranch_execz .LBB0_901
	s_load_dwordx2 s[2:3], s[2:3], 0xf8
	s_lshl_b64 s[10:11], s[0:1], 2
	v_mov_b32_e32 v1, 0xb000
	s_waitcnt lgkmcnt(0)
	s_add_u32 s2, s2, s10
	s_addc_u32 s3, s3, s11
	s_bcnt1_i32_b64 s8, s[8:9]
	s_getreg_b32 s9, hwreg(HW_REG_XCC_ID, 0, 4)
	s_mul_i32 s10, s9, s9
	s_lshl_b32 s9, s9, 8
	s_lshl_b32 s10, s10, 16
	s_or_b32 s8, s8, s9
	s_or_b32 s8, s8, s10
	v_mov_b32_e32 v0, s8
	global_atomic_add v1, v0, s[2:3] offset:1024
.LBB0_901:
	s_or_b64 exec, exec, s[4:5]
	s_mov_b64 s[4:5], s[74:75]
	s_getreg_b32 s2, hwreg(HW_REG_HW_ID, 0, 6)
	s_lshl_b32 s2, s2, 2
	s_and_b32 s2, s2, 0xfc
	s_add_i32 s2, s2, 0
	s_add_i32 s2, s2, 0x20200
	v_mov_b32_e32 v0, s2
	ds_read_b32 v0, v0
	v_mbcnt_lo_u32_b32 v1, -1, 0
	v_mbcnt_hi_u32_b32 v1, -1, v1
	s_waitcnt lgkmcnt(0)
	v_readfirstlane_b32 s2, v0
	s_lshl_b32 s2, s2, 6
	v_sub_u32_e32 v0, 0, v1
	v_cmp_eq_u32_e32 vcc, s2, v0
	s_and_saveexec_b64 s[2:3], vcc
	s_branch .LBB0_914
	s_nop 0
	s_nop 0
	s_nop 0
	s_nop 0
	s_nop 0
	s_nop 0
	s_nop 0
	s_nop 0
	s_nop 0
	s_nop 0
	s_nop 0
	s_nop 0
	s_nop 0
	s_nop 0
	s_nop 0
	s_nop 0
	s_nop 0
	s_nop 0
	s_nop 0
	s_nop 0
	s_nop 0
	s_nop 0
	s_nop 0
	s_nop 0
	s_nop 0
	s_nop 0
	s_nop 0
	s_nop 0
	s_nop 0
	s_nop 0
	s_nop 0
	s_nop 0
	s_nop 0
	s_nop 0
	s_nop 0
	s_nop 0
	s_nop 0
	s_nop 0
	s_nop 0
	s_nop 0
	s_nop 0
	s_nop 0
	s_nop 0
	s_nop 0
	s_nop 0
	s_nop 0
	s_nop 0
	s_nop 0
	s_nop 0
	s_nop 0
	s_nop 0
	s_nop 0
	s_nop 0
	s_nop 0
	s_nop 0
	s_nop 0
	s_nop 0
	s_nop 0
	s_nop 0
	s_nop 0
	s_nop 0
	s_nop 0
	s_nop 0
	s_nop 0
	s_nop 0
	s_nop 0
	s_nop 0
	s_nop 0
.LBB0_914:
	s_or_b64 exec, exec, s[2:3]
	s_mov_b64 s[8:9], s[74:75]
	s_mov_b64 s[4:5], s[74:75]
	s_mov_b64 s[2:3], s[74:75]
	s_barrier
	s_getreg_b32 s10, hwreg(HW_REG_HW_ID, 0, 6)
	s_lshl_b32 s10, s10, 2
	s_and_b32 s10, s10, 0xfc
	s_add_i32 s10, s10, 0
	s_add_i32 s10, s10, 0x20200
	v_mov_b32_e32 v0, s10
	ds_read_b32 v0, v0
	v_mbcnt_lo_u32_b32 v32, -1, 0
	v_mbcnt_hi_u32_b32 v32, -1, v32
	s_and_b64 vcc, exec, s[6:7]
	s_waitcnt lgkmcnt(0)
	v_readfirstlane_b32 s10, v0
	s_nop 1
	v_lshl_add_u32 v0, s10, 6, v32
	s_nop 0
	v_readfirstlane_b32 s12, v0
	s_cbranch_vccnz .LBB0_946
	v_lshlrev_b32_e32 v1, 4, v0
	v_add_u32_e32 v2, 0x2000, v1
	v_ashrrev_i32_e32 v3, 31, v2
	v_lshrrev_b32_e32 v3, 22, v3
	v_add_u32_e32 v3, v2, v3
	s_load_dwordx2 s[8:9], s[8:9], 0xf8
	s_nop 0
	s_load_dwordx2 s[4:5], s[4:5], 0xf8
	s_nop 0
	s_load_dwordx2 s[14:15], s[2:3], 0xf8
	v_ashrrev_i32_e32 v3, 10, v3
	v_mul_i32_i24_e32 v4, 0x400, v3
	v_sub_u32_e32 v2, v2, v4
	s_waitcnt lgkmcnt(0)
	s_add_u32 s26, s8, 0x6900000
	v_lshrrev_b32_e32 v4, 4, v2
	s_addc_u32 s27, s9, 0
	s_lshl_b64 s[2:3], s[40:41], 22
	v_bitop3_b32 v2, v4, v2, 32 bitop3:0x6c
	s_add_u32 s2, s4, s2
	v_ashrrev_i32_e32 v4, 31, v2
	s_addc_u32 s3, s5, s3
	v_lshrrev_b32_e32 v4, 26, v4
	s_add_u32 s28, s2, 0x2900000
	v_add_u32_e32 v4, v2, v4
	v_lshlrev_b32_e32 v6, 3, v3
	s_addc_u32 s29, s3, 0
	s_ashr_i32 s2, s12, 6
	v_ashrrev_i32_e32 v5, 6, v4
	v_and_b32_e32 v6, -16, v6
	v_and_b32_e32 v4, 0xc0, v4
	s_lshl_b32 s30, s2, 10
	s_lshl_b32 s2, s2, 5
	v_add_u32_e32 v6, v5, v6
	v_sub_u32_e32 v2, v2, v4
	s_and_b32 s34, s2, 0x60
	v_and_b32_e32 v5, 3, v5
	s_mov_b32 s2, 0x3fffe0
	v_lshrrev_b32_e32 v7, 2, v6
	v_lshlrev_b32_e32 v8, 1, v6
	v_lshlrev_b32_e32 v3, 5, v3
	v_ashrrev_i16_sdwa v2, v176, sext(v2) dst_sel:DWORD dst_unused:UNUSED_PAD src0_sel:DWORD src1_sel:BYTE_0
	v_and_or_b32 v5, v6, s2, v5
	v_and_b32_e32 v7, 4, v7
	v_and_b32_e32 v8, 24, v8
	v_and_b32_e32 v3, 32, v3
	v_bfe_i32 v2, v2, 0, 16
	v_or3_b32 v5, v5, v7, v8
	v_add_lshl_u32 v2, v3, v2, 1
	v_lshl_add_u32 v96, v5, 10, v2
	v_lshl_add_u32 v98, v6, 10, v2
	v_bfe_i32 v2, v0, 27, 1
	v_lshrrev_b32_e32 v2, 22, v2
	v_add_u32_e32 v2, v1, v2
	v_and_b32_e32 v2, 0xfffffc00, v2
	v_sub_u32_e32 v1, v1, v2
	v_lshrrev_b32_e32 v2, 4, v1
	v_ashrrev_i32_e32 v4, 31, v0
	v_bitop3_b32 v1, v2, v1, 32 bitop3:0x6c
	v_lshrrev_b32_e32 v4, 26, v4
	v_ashrrev_i32_e32 v2, 31, v1
	v_add_u32_e32 v0, v0, v4
	v_lshrrev_b32_e32 v2, 26, v2
	v_ashrrev_i32_e32 v0, 6, v0
	v_add_u32_e32 v2, v1, v2
	v_lshlrev_b32_e32 v4, 3, v0
	v_ashrrev_i32_e32 v3, 6, v2
	v_and_b32_e32 v4, -16, v4
	s_ashr_i32 s13, s12, 8
	v_add_u32_e32 v4, v3, v4
	v_and_b32_e32 v3, 3, v3
	s_lshl_b32 s31, s13, 6
	v_and_or_b32 v3, v4, s2, v3
	v_readlane_b32 s2, v253, 8
	v_and_b32_e32 v2, 0xc0, v2
	s_add_u32 s8, s28, s2
	s_getreg_b32 s2, hwreg(HW_REG_HW_ID, 0, 6)
	v_sub_u32_e32 v1, v1, v2
	s_addc_u32 s9, s29, 0
	s_lshl_b32 s2, s2, 2
	v_lshrrev_b32_e32 v5, 2, v4
	v_lshlrev_b32_e32 v6, 1, v4
	v_lshlrev_b32_e32 v0, 5, v0
	v_ashrrev_i16_sdwa v1, v176, sext(v1) dst_sel:DWORD dst_unused:UNUSED_PAD src0_sel:DWORD src1_sel:BYTE_0
	s_and_b32 s2, s2, 0xfc
	v_and_b32_e32 v5, 4, v5
	v_and_b32_e32 v6, 24, v6
	v_and_b32_e32 v0, 32, v0
	v_bfe_i32 v1, v1, 0, 16
	s_add_i32 s2, s2, 0
	v_or3_b32 v3, v3, v5, v6
	v_add_lshl_u32 v0, v0, v1, 1
	s_add_i32 s2, s2, 0x20200
	v_lshl_add_u32 v100, v3, 10, v0
	v_lshl_add_u32 v102, v4, 10, v0
	v_mov_b32_e32 v0, s2
	ds_read_b32 v0, v0
	v_readlane_b32 s2, v253, 10
	s_waitcnt lgkmcnt(0)
	v_mbcnt_lo_u32_b32 v0, -1, 0
	v_mbcnt_hi_u32_b32 v0, -1, v0
	s_add_i32 s35, s31, s2
	v_and_or_b32 v8, v0, 15, s35
	v_lshrrev_b32_e32 v0, 1, v0
	v_readlane_b32 s2, v253, 11
	v_ashrrev_i32_e32 v9, 31, v8
	s_mov_b32 s4, 0x100000
	v_and_or_b32 v0, v0, 24, s2
	v_or_b32_e32 v0, s34, v0
	s_add_u32 s2, s14, 0x8900000
	s_addc_u32 s3, s15, 0
	v_lshlrev_b32_e32 v136, 1, v0
	v_lshl_add_u64 v[10:11], s[2:3], 0, v[136:137]
	v_lshlrev_b64 v[0:1], 13, v[8:9]
	v_lshl_add_u64 v[24:25], v[10:11], 0, v[0:1]
	v_add_co_u32_e32 v16, vcc, s4, v24
	s_mov_b32 s4, 0x120000
	s_nop 0
	v_addc_co_u32_e32 v17, vcc, 0, v25, vcc
	v_add_co_u32_e32 v20, vcc, s4, v24
	s_mov_b32 s4, 0x140000
	s_nop 0
	v_addc_co_u32_e32 v21, vcc, 0, v25, vcc
	v_or_b32_e32 v0, 16, v8
	v_or_b32_e32 v12, 32, v8
	v_or_b32_e32 v8, 48, v8
	v_add_co_u32_e32 v26, vcc, s4, v24
	v_ashrrev_i32_e32 v1, 31, v0
	v_ashrrev_i32_e32 v13, 31, v12
	v_ashrrev_i32_e32 v9, 31, v8
	v_addc_co_u32_e32 v27, vcc, 0, v25, vcc
	s_mov_b32 s4, 0x160000
	v_lshlrev_b64 v[0:1], 13, v[0:1]
	v_lshlrev_b64 v[12:13], 13, v[12:13]
	v_lshlrev_b64 v[8:9], 13, v[8:9]
	v_add_co_u32_e32 v28, vcc, s4, v24
	s_add_i32 s36, s30, 0
	v_lshl_add_u64 v[4:5], v[10:11], 0, v[0:1]
	v_lshl_add_u64 v[12:13], v[10:11], 0, v[12:13]
	v_lshl_add_u64 v[14:15], v[10:11], 0, v[8:9]
	v_addc_co_u32_e32 v29, vcc, 0, v25, vcc
	s_add_i32 m0, s36, 0x10000
	global_load_dwordx4 v[0:3], v[24:25], off
	s_nop 0
	global_load_dwordx4 v[4:7], v[4:5], off
	s_nop 0
	global_load_dwordx4 v[8:11], v[12:13], off
	s_nop 0
	global_load_dwordx4 v[12:15], v[14:15], off
	s_nop 0
	global_load_dwordx4 v[16:19], v[16:17], off
	s_nop 0
	global_load_dwordx4 v[20:23], v[20:21], off
	s_nop 0
	global_load_dwordx4 v[24:27], v[26:27], off
	s_nop 0
	global_load_dwordx4 v[28:31], v[28:29], off
	v_readlane_b32 s4, v253, 6
	global_load_lds_dwordx4 v100, s[8:9]
	s_add_i32 m0, s36, 0x12000
	v_readlane_b32 s5, v253, 7
	s_add_u32 s10, s26, s4
	s_addc_u32 s11, s27, s5
	s_add_i32 s37, s36, 0x2000
	global_load_lds_dwordx4 v96, s[8:9]
	s_mov_b32 m0, s36
	s_add_u32 s4, s10, 0x20000
	global_load_lds_dwordx4 v102, s[10:11]
	s_mov_b32 m0, s37
	s_addc_u32 s5, s11, 0
	s_add_i32 s38, s36, 0x4000
	global_load_lds_dwordx4 v98, s[10:11]
	s_mov_b32 m0, s38
	s_add_i32 s39, s36, 0x6000
	global_load_lds_dwordx4 v102, s[4:5]
	s_mov_b32 m0, s39
	s_cmp_eq_u32 s13, 1
	global_load_lds_dwordx4 v98, s[4:5]
	v_mov_b32_e32 v197, 0xa00
	s_cselect_b64 s[4:5], -1, 0
	s_cmp_lg_u32 s13, 1
	s_cbranch_scc1 .LBB0_917
	s_barrier

.Lmy_pw1_chk:
	v_readfirstlane_b32 vcc_lo, v174
	s_and_b32 vcc_hi, vcc_lo, 0xff
	s_cmp_gt_u32 vcc_hi, 7
	s_cbranch_scc1 .Lmy_pw1_ok
	s_sleep 1
	s_load_dwordx2 vcc, s[74:75], 0xf8
	s_waitcnt lgkmcnt(0)
	s_add_u32 vcc_lo, vcc_lo, s100
	s_addc_u32 vcc_hi, vcc_hi, 0
	global_load_dword v174, v137, vcc sc1
	s_waitcnt vmcnt(0)
	s_branch .Lmy_pw1_chk
.Lmy_pw1_ok:
	s_getreg_b32 m0, hwreg(HW_REG_XCC_ID, 0, 4)
	s_bfe_u32 vcc_hi, vcc_lo, 0x80008
	s_lshr_b32 vcc_lo, vcc_lo, 16
	s_mul_i32 vcc_hi, vcc_hi, m0
	s_lshl_b32 vcc_hi, vcc_hi, 1
	s_mul_i32 m0, m0, m0
	s_lshl_b32 m0, m0, 3
	s_add_u32 vcc_lo, vcc_lo, m0
	s_cmp_eq_u32 vcc_lo, vcc_hi
	s_cbranch_scc1 .Lmy_pw1_done
	buffer_inv sc1
	s_waitcnt vmcnt(0)
.Lmy_pw1_done:
	s_nop 0
	s_nop 0
	s_nop 0
	s_nop 0
	v_lshlrev_b32_e32 v138, 16, v1
	v_and_b32_e32 v139, 0xffff0000, v1
	s_cmp_lt_u32 s46, 8
	v_pk_mul_f32 v[178:179], v[94:95], v[138:139]
	v_pk_fma_f32 v[94:95], v[94:95], v[138:139], v[170:171]
	v_lshlrev_b32_e32 v138, 16, v0
	v_and_b32_e32 v139, 0xffff0000, v0
	v_lshlrev_b32_e32 v170, 16, v2
	v_and_b32_e32 v171, 0xffff0000, v2
	v_lshlrev_b32_e32 v180, 16, v3
	v_and_b32_e32 v181, 0xffff0000, v3
	v_lshl_add_u32 v174, v136, 3, s8
	s_cselect_b64 s[8:9], -1, 0
	s_cmp_eq_u32 s15, 3
	v_pk_mul_f32 v[182:183], v[92:93], v[138:139]
	v_pk_mul_f32 v[184:185], v[88:89], v[170:171]
	v_pk_mul_f32 v[186:187], v[90:91], v[180:181]
	v_pk_fma_f32 v[92:93], v[92:93], v[138:139], v[168:169]
	v_pk_fma_f32 v[88:89], v[88:89], v[170:171], v[166:167]
	v_pk_fma_f32 v[90:91], v[90:91], v[180:181], v[162:163]
	s_cselect_b64 s[22:23], -1, 0
	s_cmp_lg_u32 s15, 3
	v_cndmask_b32_e64 v171, v95, v179, s[8:9]
	v_cndmask_b32_e64 v170, v94, v178, s[8:9]
	v_cndmask_b32_e64 v169, v93, v183, s[8:9]
	v_cndmask_b32_e64 v168, v92, v182, s[8:9]
	v_cndmask_b32_e64 v163, v91, v187, s[8:9]
	v_cndmask_b32_e64 v162, v90, v186, s[8:9]
	v_cndmask_b32_e64 v167, v89, v185, s[8:9]
	v_cndmask_b32_e64 v166, v88, v184, s[8:9]
	v_lshlrev_b32_e32 v88, 1, v174
	s_cbranch_scc1 .LBB0_926
	v_cvt_pk_bf16_f32 v90, v168, v169
	v_cvt_pk_bf16_f32 v91, v170, v171
	v_cvt_pk_bf16_f32 v92, v166, v167
	v_cvt_pk_bf16_f32 v93, v162, v163
	v_lshl_add_u32 v89, v172, 11, v88
	buffer_store_dwordx4 v[90:93], v89, s[84:87], 0 offen sc1

.LBB0_946:
	s_mov_b64 s[2:3], s[74:75]
	s_waitcnt vmcnt(0)
	s_barrier
	s_getreg_b32 s4, hwreg(HW_REG_HW_ID, 0, 6)
	s_lshl_b32 s4, s4, 2
	s_and_b32 s4, s4, 0xfc
	s_add_i32 s4, s4, 0
	s_add_i32 s4, s4, 0x20200
	s_waitcnt vmcnt(0)
	v_mov_b32_e32 v0, s4
	ds_read_b32 v0, v0
	v_mbcnt_lo_u32_b32 v1, -1, 0
	v_mbcnt_hi_u32_b32 v1, -1, v1
	s_waitcnt lgkmcnt(0)
	v_readfirstlane_b32 s4, v0
	s_lshl_b32 s4, s4, 6
	v_sub_u32_e32 v0, 0, v1
	v_cmp_eq_u32_e32 vcc, s4, v0
	s_and_saveexec_b64 s[4:5], vcc
	s_cbranch_execz .LBB0_949
	s_mov_b64 s[8:9], exec
	v_mbcnt_lo_u32_b32 v0, s8, 0
	v_mbcnt_hi_u32_b32 v0, s9, v0
	v_cmp_eq_u32_e32 vcc, 0, v0
	s_and_b64 s[10:11], exec, vcc
	s_mov_b64 exec, s[10:11]
	s_cbranch_execz .LBB0_949
	s_load_dwordx2 s[2:3], s[2:3], 0xf8
	s_lshl_b64 s[10:11], s[0:1], 2
	v_mov_b32_e32 v1, 0xc000
	s_waitcnt lgkmcnt(0)
	s_add_u32 s2, s2, s10
	s_addc_u32 s3, s3, s11
	s_bcnt1_i32_b64 s8, s[8:9]
	s_getreg_b32 s9, hwreg(HW_REG_XCC_ID, 0, 4)
	s_mul_i32 s10, s9, s9
	s_lshl_b32 s9, s9, 8
	s_lshl_b32 s10, s10, 16
	s_or_b32 s8, s8, s9
	s_or_b32 s8, s8, s10
	v_mov_b32_e32 v0, s8
	global_atomic_add v1, v0, s[2:3] offset:2048
.LBB0_949:
	s_or_b64 exec, exec, s[4:5]
	s_mov_b64 s[4:5], s[74:75]
	s_getreg_b32 s2, hwreg(HW_REG_HW_ID, 0, 6)
	s_lshl_b32 s2, s2, 2
	s_and_b32 s2, s2, 0xfc
	s_add_i32 s2, s2, 0
	s_add_i32 s2, s2, 0x20200
	v_mov_b32_e32 v0, s2
	ds_read_b32 v0, v0
	v_mbcnt_lo_u32_b32 v1, -1, 0
	v_mbcnt_hi_u32_b32 v1, -1, v1
	s_waitcnt lgkmcnt(0)
	v_readfirstlane_b32 s2, v0
	s_lshl_b32 s2, s2, 6
	v_sub_u32_e32 v0, 0, v1
	v_cmp_eq_u32_e32 vcc, s2, v0
	s_and_saveexec_b64 s[2:3], vcc
	s_branch .LBB0_962
	s_nop 0
	s_nop 0
	s_nop 0
	s_nop 0
	s_nop 0
	s_nop 0
	s_nop 0
	s_nop 0
	s_nop 0
	s_nop 0
.LBB0_962:
	s_or_b64 exec, exec, s[2:3]
	s_mov_b64 s[2:3], s[74:75]
	s_mov_b64 s[8:9], s[74:75]
	s_mov_b64 s[0:1], s[74:75]
	s_mov_b64 s[12:13], s[74:75]
	s_barrier
	s_getreg_b32 s4, hwreg(HW_REG_HW_ID, 0, 6)
	s_lshl_b32 s4, s4, 2
	s_and_b32 s4, s4, 0xfc
	s_add_i32 s4, s4, 0
	s_add_i32 s4, s4, 0x20200
	v_mov_b32_e32 v0, s4
	ds_read_b32 v0, v0
	v_mbcnt_lo_u32_b32 v56, -1, 0
	v_mbcnt_hi_u32_b32 v56, -1, v56
	s_and_b64 vcc, exec, s[6:7]
	s_waitcnt lgkmcnt(0)
	v_readfirstlane_b32 s4, v0
	s_nop 1
	v_lshl_add_u32 v30, s4, 6, v56
	s_nop 0
	v_readfirstlane_b32 s17, v30
	s_cbranch_vccnz .LBB0_1074
	s_load_dwordx2 s[4:5], s[2:3], 0xf8
	s_nop 0
	s_load_dwordx2 s[2:3], s[8:9], 0xf8
	s_nop 0
	s_load_dwordx4 s[8:11], s[12:13], 0xf0
	s_getreg_b32 s6, hwreg(HW_REG_HW_ID, 0, 6)
	s_lshl_b32 s6, s6, 2
	s_and_b32 s6, s6, 0xfc
	s_add_i32 s6, s6, 0
	s_add_i32 s6, s6, 0x20200
	v_mov_b32_e32 v0, s6
	s_ashr_i32 s20, s17, 8
	ds_read_b32 v0, v0
	s_lshl_b32 s16, s20, 6
	v_readlane_b32 s12, v253, 61
	v_mbcnt_lo_u32_b32 v4, -1, 0
	v_mbcnt_hi_u32_b32 v4, -1, v4
	v_readlane_b32 s6, v253, 9
	s_waitcnt lgkmcnt(0)
	v_and_or_b32 v0, v4, 15, s16
	v_readlane_b32 s13, v253, 62
	v_add_u32_e32 v24, s6, v0
	s_mov_b64 s[6:7], -1
	s_and_b64 vcc, exec, s[12:13]
	s_cbranch_vccz .LBB0_965
	v_ashrrev_i32_e32 v25, 31, v24
	s_mov_b64 s[6:7], 0
	v_mov_b64_e32 v[0:1], v[24:25]

.Lmy_pw2_poll:
	s_load_dwordx2 vcc, s[74:75], 0xf8
	s_waitcnt lgkmcnt(0)
	s_add_u32 vcc_lo, vcc_lo, s100
	s_addc_u32 vcc_hi, vcc_hi, 0
	s_add_u32 vcc_lo, vcc_lo, 0x1400
	s_addc_u32 vcc_hi, vcc_hi, 0
	global_load_dword v138, v137, vcc sc1
	s_waitcnt vmcnt(0)
	v_readfirstlane_b32 vcc_lo, v138
	s_and_b32 vcc_hi, vcc_lo, 0xff
	s_cmp_gt_u32 vcc_hi, 7
	s_cbranch_scc1 .Lmy_pw2_ok
	s_sleep 1
	s_branch .Lmy_pw2_poll
